# c8 plus grid barrier where the last XCD leader bumps all eight per-XCD generation words (one poll hop less)
# speedup vs baseline: 1.0018x; 1.0018x over previous
; __device__ __forceinline__ unsigned xb_ld(unsigned* p)              { return __hip_atomic_load(p, __ATOMIC_RELAXED, __HIP_MEMORY_SCOPE_AGENT); }
; __device__ __forceinline__ unsigned xb_add(unsigned* p, unsigned v) { return __hip_atomic_fetch_add(p, v, __ATOMIC_RELAXED, __HIP_MEMORY_SCOPE_AGENT); }
; #define XB_SPIN(cond, bar) do { unsigned _sp = 0; while (cond) { __builtin_amdgcn_s_sleep(1); \
;     if ((++_sp & 255u) == 0u) { if (xb_ld(&(bar)[XB_TMO])) break; if (_sp > XB_SPIN_CAP) { atomicAdd(&(bar)[XB_TMO], 1u); break; } } } } while (0)
; __device__ __forceinline__ void xcd_barrier(const XcdBarrier& b) {
;     ...
;             if (og + 1u == (tg + 1u) * nx) xb_add(&bar[XB_TOPGEN], 1u);
;             else XB_SPIN(xb_ld(&bar[XB_TOPGEN]) == tg, bar);
;             __builtin_amdgcn_fence(__ATOMIC_ACQUIRE, "agent");
;             xb_add(&bar[XB_XGEN(b.x)], 1u);
;             asm volatile("s_waitcnt vmcnt(0)" ::: "memory");
.LBB0_118:
	s_or_b64 exec, exec, s[18:19]
	v_readlane_b32 s0, v251, 22
	v_readlane_b32 s1, v251, 23
	v_mov_b32_e32 v1, 1
	v_cmp_eq_u32_e32 vcc, 1, v7
	s_add_u32 s0, s0, 0x2200
	s_addc_u32 s1, s1, 0
	s_and_saveexec_b64 s[18:19], vcc
	s_cbranch_execz .Lxg8_1
	global_atomic_add v131, v1, s[0:1]
	global_atomic_add v131, v1, s[0:1] offset:256
	global_atomic_add v131, v1, s[0:1] offset:512
	global_atomic_add v131, v1, s[0:1] offset:768
	global_atomic_add v131, v1, s[0:1] offset:1024
	global_atomic_add v131, v1, s[0:1] offset:1280
	global_atomic_add v131, v1, s[0:1] offset:1536
	global_atomic_add v131, v1, s[0:1] offset:1792
.Lxg8_1:
	s_or_b64 exec, exec, s[18:19]
	buffer_inv sc1
	s_waitcnt vmcnt(0)

; __device__ __forceinline__ unsigned xb_ld(unsigned* p)              { return __hip_atomic_load(p, __ATOMIC_RELAXED, __HIP_MEMORY_SCOPE_AGENT); }
; __device__ __forceinline__ unsigned xb_add(unsigned* p, unsigned v) { return __hip_atomic_fetch_add(p, v, __ATOMIC_RELAXED, __HIP_MEMORY_SCOPE_AGENT); }
; #define XB_SPIN(cond, bar) do { unsigned _sp = 0; while (cond) { __builtin_amdgcn_s_sleep(1); \
;     if ((++_sp & 255u) == 0u) { if (xb_ld(&(bar)[XB_TMO])) break; if (_sp > XB_SPIN_CAP) { atomicAdd(&(bar)[XB_TMO], 1u); break; } } } } while (0)
; __device__ __forceinline__ void xcd_barrier(const XcdBarrier& b) {
;     ...
;             const unsigned og = xb_add(&bar[XB_TOP], 1u);
;             const unsigned tg = og / nx;
;             if (og + 1u == (tg + 1u) * nx) xb_add(&bar[XB_TOPGEN], 1u);
;             else XB_SPIN(xb_ld(&bar[XB_TOPGEN]) == tg, bar);
.LBB0_206:
	s_or_b64 exec, exec, s[20:21]
	s_waitcnt vmcnt(0)
	v_readfirstlane_b32 s0, v3
	v_sub_u32_e32 v4, 0, v2
	s_mov_b64 s[20:21], -1
	v_add_u32_e32 v3, s0, v1
	v_cvt_f32_u32_e32 v1, v2
	v_readlane_b32 s0, v252, 30
	v_readlane_b32 s1, v252, 31
	v_rcp_iflag_f32_e32 v1, v1
	s_nop 0
	v_mul_f32_e32 v1, 0x4f7ffffe, v1
	v_cvt_u32_f32_e32 v1, v1
	v_mul_lo_u32 v4, v4, v1
	v_mul_hi_u32 v4, v1, v4
	v_add_u32_e32 v1, v1, v4
	v_mul_hi_u32 v1, v3, v1
	v_mul_lo_u32 v4, v1, v2
	v_sub_u32_e32 v4, v3, v4
	v_cmp_ge_u32_e32 vcc, v4, v2
	v_add_u32_e32 v5, 1, v1
	v_add_u32_e32 v3, 1, v3
	v_cndmask_b32_e32 v1, v1, v5, vcc
	v_sub_u32_e32 v5, v4, v2
	v_cndmask_b32_e32 v4, v4, v5, vcc
	v_cmp_ge_u32_e32 vcc, v4, v2
	v_add_u32_e32 v4, 1, v1
	s_nop 0
	v_cndmask_b32_e32 v1, v1, v4, vcc
	v_mul_lo_u32 v4, v2, v1
	v_add_u32_e32 v2, v4, v2
	v_cmp_ne_u32_e32 vcc, v3, v2
	s_nop 1
	v_cndmask_b32_e64 v7, 1, 0, vcc
	v_mov_b64_e32 v[2:3], s[0:1]
	s_and_saveexec_b64 s[18:19], vcc
	s_cbranch_execz .LBB0_218
	v_readlane_b32 s0, v252, 30
	v_readlane_b32 s1, v252, 31
	s_mov_b64 s[22:23], 0
	s_nop 3
	global_load_dword v2, v131, s[0:1] sc1
	s_waitcnt vmcnt(0)
	v_cmp_eq_u32_e32 vcc, v2, v1
	s_and_saveexec_b64 s[20:21], vcc
	s_cbranch_execz .LBB0_217
	s_mov_b32 s0, 1
	s_branch .LBB0_210
